# late weight conversion split over the compress phase (idle workgroups take up to 4 item pairs) and the attention phase
# speedup vs baseline: 1.0095x; 1.0095x over previous
; DEVI int vblk() { return (int)blockIdx.x * 2 + vhalf(); }
; DEVI int vgrid() { return (int)gridDim.x * 2; }
; DEVI void phase1(const Params& p, int l, char* lds) {
;     ...
;   for (int item = vblk(); item < n_items; item += vgrid()) {
;     int i = item;
;     if (i < P1_CVT) {
.LBB0_781:
	v_readlane_b32 s0, v244, 57
	v_readlane_b32 s1, v244, 58
	s_load_dword s0, s[0:1], 0x0
	s_waitcnt lgkmcnt(0)
	s_lshl_b32 s0, s0, 1
	s_add_i32 s23, s0, s23
	s_cmp_ge_i32 s23, s20
	s_cbranch_scc0 .Lp1_more
	s_cmp_eq_u32 s101, 0x5a5a
	s_cbranch_scc1 .Lcv_ret
	s_cmp_eq_u32 s101, 0x5a5b
	s_cbranch_scc1 .Lcv3a_ret
	s_branch .LBB0_915
.Lp1_more:
.LBB0_782:
	s_or_b32 vcc_lo, s101, 1
	s_cmp_eq_u32 vcc_lo, 0x5a5b
	s_cbranch_scc1 .Lp1_noskip
	s_cmpk_lt_i32 s23, 0x300
	s_cbranch_scc1 .Lp1_noskip
	s_cmpk_lt_i32 s23, 0x1100
	s_cbranch_scc1 .LBB0_781

; DEVI int vblk() { return (int)blockIdx.x * 2 + vhalf(); }
; DEVI int vgrid() { return (int)gridDim.x * 2; }
; DEVI void phase3a(const Params& p, int l, char* lds, bool rep, volatile int* nsa_cnt) {
;   const int v = vblk(), nv = vgrid();
;   const int wg = (int)blockIdx.x, nwg = (int)gridDim.x;
;   if (wg < P3_CMP) {
;     for (int i = wg; i < P3_CMP; i += nwg) compress_item(p, l, i, lds);
;     if (nwg > 2 * P3_CMP) return;
;   }
;   const bool split = (nwg > 2 * P3_CMP);
;   const int first = split ? v - 2 * P3_CMP : v, step = split ? nv - 2 * P3_CMP : nv;
;   for (int item = first; item < P3_PRE; item += step) prepass_item(p, l, item, lds);
;   if (split && !rep) pull_extras(p, l, lds, nsa_cnt, 1);
; }
.LBB0_914:
	s_or_b64 exec, exec, s[0:1]
	s_mov_b32 s0, 4
	v_writelane_b32 v245, s0, 2

; DEVI int vhalf() { int t = threadIdx.x >> 8; t = __builtin_amdgcn_readfirstlane(t); return t; }
; DEVI void pull_extras(const Params& p, int l, char* lds, volatile int* nsa_cnt, int max_pulls) {
;   unsigned* q = (unsigned*)(p.ws + OFF_BAR) + 3500 + l;
;   for (int n = 0; n < max_pulls; ++n) {
;     __syncthreads();
;     if (threadIdx.x == 0) nsa_cnt[2] = (int)atomicAdd(q, 2u);
;     __syncthreads();
;     const int base = nsa_cnt[2];
;     if (base >= P3B_EXTRA) break;
;     int i = base + vhalf();
.Lcv3a_bcast:
	s_or_b64 exec, exec, s[36:37]
	s_waitcnt lgkmcnt(0)
	s_barrier
	v_mov_b32_e32 v2, 0xc1c
	ds_read_b32 v2, v2
	s_waitcnt lgkmcnt(0)
	v_readfirstlane_b32 s23, v2
	s_cmpk_ge_u32 s23, 0xe00
	s_cbranch_scc1 .Lcv3a_done
	v_readfirstlane_b32 s0, v220
	s_lshr_b32 s0, s0, 8
	s_add_i32 s23, s23, s0
	s_addk_i32 s23, 0x300
	s_add_i32 s20, s23, 1
	s_mov_b32 s101, 0x5a5b
	s_mov_b64 s[0:1], 0
	s_branch .Lp1_entry
.Lcv3a_ret:
	s_mov_b32 s101, 0
	v_readlane_b32 s0, v245, 2
	s_sub_u32 s0, s0, 1
	v_writelane_b32 v245, s0, 2
	s_cmp_eq_u32 s0, 0
	s_cbranch_scc0 .Lcv3a_loop
.Lcv3a_done:
	s_mov_b32 s101, 0
	s_cbranch_execz .LBB0_672
